# v67 + residual-norm phases: rows dealt per XCD (XCD x owns prompt rows 4096x..4096x+4095 and 64 sample rows, same 18/10 balance) so each XCD reads the rows its GEMM tiles wrote
# speedup vs baseline: 1.0031x; 1.0031x over previous
.LBB0_452:
	v_readlane_b32 s24, v255, 2
	v_readlane_b32 s25, v255, 3
	s_ashr_i32 s29, s2, 6
	s_mov_b64 s[2:3], s[24:25]
	s_load_dwordx2 s[6:7], s[2:3], 0x0
	s_mov_b64 s[2:3], s[24:25]
	s_mov_b64 s[8:9], s[24:25]
	s_mov_b64 s[12:13], s[24:25]
	s_load_dwordx2 s[8:9], s[8:9], 0xf0
	s_mov_b64 s[14:15], s[24:25]
	s_load_dwordx2 s[12:13], s[12:13], 0xf0
	s_load_dwordx2 s[14:15], s[14:15], 0xf0
	s_lshl_b32 s33, s11, 3
	s_add_i32 s50, s33, s29
	s_lshl_b32 s18, s10, 3
	s_mov_b64 s[10:11], s[24:25]
	s_waitcnt lgkmcnt(0)
	s_add_u32 s48, s14, 0x100000
	s_addc_u32 s49, s15, 0
	s_mov_b64 s[14:15], s[24:25]
	s_load_dwordx2 s[10:11], s[10:11], 0x50
	s_mov_b64 s[16:17], s[24:25]
	s_load_dwordx2 s[14:15], s[14:15], 0xf0
	s_load_dwordx2 s[16:17], s[16:17], 0x50
	s_waitcnt lgkmcnt(0)
	s_add_u32 s10, s10, 0x1000
	s_addc_u32 s11, s11, 0
	s_waitcnt vmcnt(0)
	v_and_b32_e32 v24, 63, v0
	s_mov_b64 s[20:21], 0x2000
	s_add_u32 s16, s16, 0x2000
	s_addc_u32 s17, s17, 0
	s_and_b32 s98, s50, 0xff
	s_lshr_b32 s99, s50, 8
	s_lshl_b32 s99, s99, 6
	s_sub_i32 s19, 0xff, s98
	s_add_i32 s19, s19, s99
	s_cmpk_lt_u32 s98, 0xc0
	s_cselect_b32 s19, 0x200, s19
	s_add_i32 s22, s19, 0x8000
	s_cmp_gt_i32 s22, 0x81ff
	v_lshlrev_b32_e32 v120, 4, v24
	s_cbranch_scc1 .LBB0_455
	v_mbcnt_lo_u32_b32 v0, -1, 0
	v_mbcnt_hi_u32_b32 v0, -1, v0
	v_and_b32_e32 v1, 64, v0
	v_add_u32_e32 v1, 64, v1
	v_xor_b32_e32 v2, 1, v0
	v_cmp_lt_i32_e32 vcc, v2, v1
	s_ashr_i32 s23, s22, 31
	s_load_dwordx2 s[34:35], s[2:3], 0x8
	s_load_dwordx2 s[42:43], s[24:25], 0xf0
	v_cndmask_b32_e32 v2, v0, v2, vcc
	v_lshlrev_b32_e32 v25, 2, v2
	v_xor_b32_e32 v2, 2, v0
	v_cmp_lt_i32_e32 vcc, v2, v1
	s_lshl_b64 s[2:3], s[22:23], 11
	s_add_u32 s24, s14, s2
	v_cndmask_b32_e32 v2, v0, v2, vcc
	v_lshlrev_b32_e32 v36, 2, v2
	v_xor_b32_e32 v2, 4, v0
	v_cmp_lt_i32_e32 vcc, v2, v1
	s_addc_u32 s25, s15, s3
	s_ashr_i32 s19, s18, 31
	v_cndmask_b32_e32 v2, v0, v2, vcc
	s_lshl_b64 s[26:27], s[18:19], 11
	v_lshlrev_b32_e32 v37, 2, v2
	v_xor_b32_e32 v2, 8, v0
	s_add_u32 s36, s12, s2
	v_cmp_lt_i32_e32 vcc, v2, v1
	s_addc_u32 s37, s13, s3
	s_add_i32 s2, s22, 0xffff8000
	v_cndmask_b32_e32 v2, v0, v2, vcc
	v_lshlrev_b32_e32 v38, 2, v2
	v_xor_b32_e32 v2, 16, v0
	v_cmp_lt_i32_e32 vcc, v2, v1
	s_ashr_i32 s3, s2, 31
	s_lshl_b64 s[2:3], s[2:3], 12
	v_cndmask_b32_e32 v2, v0, v2, vcc
	v_lshlrev_b32_e32 v39, 2, v2
	v_xor_b32_e32 v2, 32, v0
	s_waitcnt lgkmcnt(0)
	s_add_u32 s38, s34, s2
	v_cmp_lt_i32_e32 vcc, v2, v1
	s_addc_u32 s39, s35, s3
	s_lshl_b64 s[40:41], s[18:19], 12
	v_cndmask_b32_e32 v0, v0, v2, vcc
	v_mov_b32_e32 v121, 0
	s_add_u32 s42, s42, s2
	v_lshlrev_b32_e32 v40, 2, v0
	v_lshl_add_u64 v[20:21], s[10:11], 0, v[120:121]
	v_lshl_add_u64 v[22:23], s[16:17], 0, v[120:121]
	v_lshlrev_b32_e32 v26, 3, v24
	v_mov_b32_e32 v27, v121
	s_addc_u32 s43, s43, s3
	s_mov_b32 s19, 0x52800000
	s_mov_b32 s23, 0x52a00000
	s_mov_b32 s51, 0x52c00000
	s_mov_b32 s52, 0x52e00000
	s_mov_b32 s53, 0x53000000
	s_mov_b32 s54, 0x53200000
	s_mov_b32 s55, 0x53400000
	s_mov_b32 s56, 0x53600000
	s_mov_b32 s57, 0x53800000
	s_mov_b32 s58, 0x53a00000
	s_mov_b32 s59, 0x53c00000
	s_mov_b32 s60, 0x53e00000
	v_mov_b32_e32 v41, 0x358637bd
	s_mov_b32 s61, 0xf800000
	v_mov_b32_e32 v42, 0x260
	v_lshlrev_b32_e32 v28, 4, v24
	v_mov_b32_e32 v29, v121
	s_brev_b32 s62, 42
	s_mov_b64 s[44:45], 0x4000
	s_movk_i32 s63, 0x4000
	s_mov_b64 s[46:47], 0x3000
	s_movk_i32 s64, 0x3000
	s_mov_b32 s65, 0x9000000

.LBB0_455:
	s_add_u32 s2, s8, 0xd100000
	s_addc_u32 s3, s9, 0
	s_abs_i32 s19, s18
	v_cvt_f32_u32_e32 v0, s19
	s_add_i32 s20, s18, 0x7fff
	s_sub_i32 s21, 0xffff8001, s18
	s_xor_b32 s18, s20, s18
	v_rcp_iflag_f32_e32 v0, v0
	s_max_i32 s20, s20, s21
	s_sub_i32 s21, 0, s19
	s_ashr_i32 s18, s18, 31
	v_mul_f32_e32 v0, 0x4f7ffffe, v0
	v_cvt_u32_f32_e32 v0, v0
	v_lshlrev_b32_e32 v122, 5, v24
	v_readfirstlane_b32 s22, v0
	s_mul_i32 s21, s21, s22
	s_mul_hi_u32 s21, s22, s21
	s_add_i32 s22, s22, s21
	s_mul_hi_u32 s21, s20, s22
	s_mul_i32 s22, s21, s19
	s_sub_i32 s20, s20, s22
	s_add_i32 s23, s21, 1
	s_sub_i32 s22, s20, s19
	s_cmp_ge_u32 s20, s19
	s_cselect_b32 s21, s23, s21
	s_cselect_b32 s20, s22, s20
	s_add_i32 s22, s21, 1
	s_cmp_ge_u32 s20, s19
	s_cselect_b32 s19, s22, s21
	s_xor_b32 s19, s19, s18
	s_sub_i32 s19, s19, s18
	s_mul_i32 s18, s19, s50
	s_add_i32 s19, s18, s19
	s_min_i32 s24, s19, 0x8000
	s_and_b32 s100, s50, 0xff
	s_lshr_b32 s101, s50, 8
	s_lshl_b32 s101, s101, 12
	s_mul_i32 s98, s100, 18
	s_add_i32 s98, s98, s101
	s_add_i32 s99, s100, 0xffffff40
	s_mul_i32 s99, s99, 10
	s_addk_i32 s99, 0xd80
	s_add_i32 s99, s99, s101
	s_cmpk_lt_i32 s100, 0xc0
	s_cselect_b32 s18, s98, s99
	s_cselect_b32 s98, 18, 10
	s_add_i32 s24, s18, s98
	s_cmp_lt_i32 s18, s24
	s_cselect_b64 s[20:21], -1, 0
	s_cmp_ge_i32 s18, s24
	s_cbranch_scc1 .LBB0_458
	s_ashr_i32 s19, s18, 31
	s_lshl_b64 s[22:23], s[18:19], 12
	s_add_u32 s22, s6, s22
	s_addc_u32 s23, s7, s23
	global_load_dwordx4 v[100:103], v122, s[22:23] offset:16
	global_load_dwordx4 v[108:111], v122, s[22:23]
	global_load_dwordx4 v[96:99], v122, s[22:23] offset:2064
	global_load_dwordx4 v[104:107], v122, s[22:23] offset:2048
	s_lshl_b64 s[22:23], s[18:19], 11
	s_add_u32 s22, s2, s22
	s_addc_u32 s23, s3, s23
	global_load_dwordx4 v[116:119], v120, s[22:23]
	global_load_dwordx4 v[112:115], v120, s[22:23] offset:1024
	s_add_i32 s22, s18, 1
	s_cmp_ge_i32 s22, s24
	s_cbranch_scc0 .LBB0_459

.LBB0_671:
	v_readlane_b32 s20, v255, 2
	v_readlane_b32 s21, v255, 3
	s_lshl_b32 s48, s3, 3
	s_lshl_b32 s18, s2, 3
	s_mov_b64 s[2:3], s[20:21]
	s_load_dwordx2 s[12:13], s[2:3], 0xf0
	s_mov_b64 s[2:3], s[20:21]
	s_load_dwordx2 s[14:15], s[2:3], 0xf0
	s_mov_b64 s[2:3], s[20:21]
	s_load_dwordx2 s[10:11], s[2:3], 0xf0
	s_mov_b64 s[2:3], s[20:21]
	s_ashr_i32 s6, s6, 6
	s_add_i32 s48, s48, s6
	s_load_dwordx2 s[2:3], s[2:3], 0xf0
	s_mov_b64 s[6:7], s[20:21]
	s_mov_b64 s[8:9], s[20:21]
	s_load_dwordx2 s[6:7], s[6:7], 0x50
	s_mov_b64 s[16:17], s[20:21]
	s_load_dwordx2 s[8:9], s[8:9], 0xf0
	s_load_dwordx2 s[16:17], s[16:17], 0x50
	s_waitcnt lgkmcnt(0)
	s_add_u32 s46, s2, 0x100000
	s_addc_u32 s47, s3, 0
	s_add_u32 s6, s6, 0x3000
	s_addc_u32 s7, s7, 0
	s_add_u32 s16, s16, 0x4000
	s_addc_u32 s17, s17, 0
	s_and_b32 s98, s48, 0xff
	s_lshr_b32 s99, s48, 8
	s_lshl_b32 s99, s99, 6
	s_sub_i32 s19, 0xff, s98
	s_add_i32 s19, s19, s99
	s_cmpk_lt_u32 s98, 0xc0
	s_cselect_b32 s19, 0x200, s19
	v_and_b32_e32 v16, 63, v0
	s_mov_b64 s[2:3], s[20:21]
	s_add_i32 s20, s19, 0x8000
	s_cmp_gt_i32 s20, 0x81ff
	v_lshlrev_b32_e32 v96, 4, v16
	s_cbranch_scc1 .LBB0_674
	v_mbcnt_lo_u32_b32 v0, -1, 0
	v_mbcnt_hi_u32_b32 v0, -1, v0
	v_and_b32_e32 v1, 64, v0
	v_add_u32_e32 v1, 64, v1
	v_xor_b32_e32 v2, 1, v0
	v_cmp_lt_i32_e32 vcc, v2, v1
	s_load_dwordx2 s[2:3], s[2:3], 0xf0
	v_mov_b32_e32 v97, 0
	v_cndmask_b32_e32 v2, v0, v2, vcc
	v_lshlrev_b32_e32 v17, 2, v2
	v_xor_b32_e32 v2, 2, v0
	v_cmp_lt_i32_e32 vcc, v2, v1
	s_ashr_i32 s21, s20, 31
	v_lshl_add_u64 v[4:5], s[6:7], 0, v[96:97]
	v_cndmask_b32_e32 v2, v0, v2, vcc
	v_lshlrev_b32_e32 v34, 2, v2
	v_xor_b32_e32 v2, 4, v0
	v_cmp_lt_i32_e32 vcc, v2, v1
	v_lshl_add_u64 v[6:7], s[16:17], 0, v[96:97]
	v_lshlrev_b32_e32 v10, 3, v16
	v_cndmask_b32_e32 v2, v0, v2, vcc
	v_lshlrev_b32_e32 v35, 2, v2
	v_xor_b32_e32 v2, 8, v0
	v_cmp_lt_i32_e32 vcc, v2, v1
	v_mov_b32_e32 v11, v97
	s_mov_b32 s49, 0x400000
	v_cndmask_b32_e32 v2, v0, v2, vcc
	v_lshlrev_b32_e32 v36, 2, v2
	v_xor_b32_e32 v2, 16, v0
	v_cmp_lt_i32_e32 vcc, v2, v1
	s_mov_b32 s50, 0x600000
	s_mov_b32 s51, 0x800000
	v_cndmask_b32_e32 v2, v0, v2, vcc
	v_lshlrev_b32_e32 v37, 2, v2
	v_xor_b32_e32 v2, 32, v0
	v_cmp_lt_i32_e32 vcc, v2, v1
	s_mov_b32 s52, 0xa00000
	s_mov_b32 s53, 0xc00000
	v_cndmask_b32_e32 v0, v0, v2, vcc
	v_lshlrev_b32_e32 v38, 2, v0
	s_waitcnt lgkmcnt(0)
	v_lshl_add_u64 v[0:1], s[2:3], 0, v[96:97]
	s_mov_b64 s[2:3], 0x52800000
	v_lshl_add_u64 v[8:9], v[0:1], 0, s[2:3]
	s_lshl_b64 s[2:3], s[20:21], 11
	s_add_u32 s22, s8, s2
	s_addc_u32 s23, s9, s3
	s_ashr_i32 s19, s18, 31
	s_lshl_b64 s[24:25], s[18:19], 11
	s_add_u32 s26, s10, s2
	s_addc_u32 s27, s11, s3
	s_add_u32 s36, s12, s2
	s_addc_u32 s37, s13, s3
	s_brev_b32 s19, 42
	s_mov_b32 s21, 0x200000
	s_mov_b32 s54, 0xe00000
	s_mov_b32 s55, 0x1000000
	s_mov_b32 s56, 0x1200000
	s_mov_b32 s57, 0x1400000
	v_mov_b32_e32 v39, 0x358637bd
	s_mov_b32 s58, 0xf800000
	v_mov_b32_e32 v40, 0x260
	v_lshlrev_b32_e32 v12, 4, v16
	v_mov_b32_e32 v13, v97
	s_mov_b64 s[38:39], 0x5000
	s_movk_i32 s59, 0x5000
	s_mov_b64 s[40:41], 0xd9000
	s_mov_b32 s60, 0xd9000
	s_mov_b64 s[42:43], 0xd8000
	s_mov_b32 s61, 0xd8000
	s_mov_b32 s62, 0x9000000

.LBB0_674:
	s_add_u32 s2, s12, 0x54000000
	s_addc_u32 s3, s13, 0
	s_add_u32 s20, s14, 0xd100000
	s_addc_u32 s21, s15, 0
	s_abs_i32 s19, s18
	v_cvt_f32_u32_e32 v0, s19
	s_add_i32 s22, s18, 0x7fff
	s_sub_i32 s23, 0xffff8001, s18
	s_xor_b32 s18, s22, s18
	v_rcp_iflag_f32_e32 v0, v0
	s_max_i32 s22, s22, s23
	s_sub_i32 s23, 0, s19
	s_ashr_i32 s18, s18, 31
	v_mul_f32_e32 v0, 0x4f7ffffe, v0
	v_cvt_u32_f32_e32 v0, v0
	s_nop 0
	v_readfirstlane_b32 s24, v0
	s_mul_i32 s23, s23, s24
	s_mul_hi_u32 s23, s24, s23
	s_add_i32 s24, s24, s23
	s_mul_hi_u32 s23, s22, s24
	s_mul_i32 s24, s23, s19
	s_sub_i32 s22, s22, s24
	s_add_i32 s25, s23, 1
	s_sub_i32 s24, s22, s19
	s_cmp_ge_u32 s22, s19
	s_cselect_b32 s23, s25, s23
	s_cselect_b32 s22, s24, s22
	s_add_i32 s24, s23, 1
	s_cmp_ge_u32 s22, s19
	s_cselect_b32 s19, s24, s23
	s_xor_b32 s19, s19, s18
	s_sub_i32 s19, s19, s18
	s_mul_i32 s18, s19, s48
	s_add_i32 s19, s18, s19
	s_min_i32 s26, s19, 0x8000
	s_and_b32 s100, s48, 0xff
	s_lshr_b32 s101, s48, 8
	s_lshl_b32 s101, s101, 12
	s_mul_i32 s98, s100, 18
	s_add_i32 s98, s98, s101
	s_add_i32 s99, s100, 0xffffff40
	s_mul_i32 s99, s99, 10
	s_addk_i32 s99, 0xd80
	s_add_i32 s99, s99, s101
	s_cmpk_lt_i32 s100, 0xc0
	s_cselect_b32 s18, s98, s99
	s_cselect_b32 s98, 18, 10
	s_add_i32 s26, s18, s98
	s_cmp_lt_i32 s18, s26
	s_cselect_b64 s[22:23], -1, 0
	s_cmp_ge_i32 s18, s26
	s_cbranch_scc1 .LBB0_676
	s_ashr_i32 s19, s18, 31
	s_lshl_b64 s[24:25], s[18:19], 11
	s_add_u32 s34, s20, s24
	s_addc_u32 s35, s21, s25
	s_add_u32 s24, s2, s24
	s_addc_u32 s25, s3, s25
	global_load_dwordx4 v[84:87], v96, s[24:25]
	global_load_dwordx4 v[80:83], v96, s[24:25] offset:1024
	global_load_dwordx4 v[92:95], v96, s[34:35]
	global_load_dwordx4 v[88:91], v96, s[34:35] offset:1024

.LBB0_1176:
	v_readlane_b32 s20, v255, 2
	v_readlane_b32 s21, v255, 3
	s_lshl_b32 s34, s3, 3
	s_lshl_b32 s18, s2, 3
	s_mov_b64 s[2:3], s[20:21]
	s_load_dwordx2 s[12:13], s[2:3], 0xf0
	s_mov_b64 s[2:3], s[20:21]
	s_load_dwordx2 s[14:15], s[2:3], 0xf0
	s_mov_b64 s[2:3], s[20:21]
	s_load_dwordx2 s[10:11], s[2:3], 0xf0
	s_mov_b64 s[2:3], s[20:21]
	s_ashr_i32 s6, s6, 6
	s_add_i32 s34, s34, s6
	s_load_dwordx2 s[2:3], s[2:3], 0xf0
	s_mov_b64 s[6:7], s[20:21]
	s_mov_b64 s[8:9], s[20:21]
	s_load_dwordx2 s[6:7], s[6:7], 0x50
	s_mov_b64 s[16:17], s[20:21]
	s_load_dwordx2 s[8:9], s[8:9], 0xf0
	s_load_dwordx2 s[16:17], s[16:17], 0x50
	s_waitcnt lgkmcnt(0)
	s_add_u32 s52, s2, 0x100000
	s_addc_u32 s53, s3, 0
	s_add_u32 s6, s6, 0x5000
	s_addc_u32 s7, s7, 0
	s_add_u32 s16, s16, 0x6000
	s_addc_u32 s17, s17, 0
	s_and_b32 s98, s34, 0xff
	s_lshr_b32 s99, s34, 8
	s_lshl_b32 s99, s99, 6
	s_sub_i32 s19, 0xff, s98
	s_add_i32 s19, s19, s99
	s_cmpk_lt_u32 s98, 0xc0
	s_cselect_b32 s19, 0x200, s19
	v_and_b32_e32 v16, 63, v0
	s_mov_b64 s[2:3], s[20:21]
	s_add_i32 s20, s19, 0x8000
	s_cmp_gt_i32 s20, 0x81ff
	v_lshlrev_b32_e32 v96, 4, v16
	s_cbranch_scc1 .LBB0_1179
	v_mbcnt_hi_u32_b32 v0, -1, v252
	v_and_b32_e32 v1, 64, v0
	v_xor_b32_e32 v2, 1, v0
	v_add_u32_e32 v1, 64, v1
	v_cmp_lt_i32_e32 vcc, v2, v1
	s_load_dwordx2 s[2:3], s[2:3], 0xf0
	v_mov_b32_e32 v97, 0
	v_cndmask_b32_e32 v2, v0, v2, vcc
	v_lshlrev_b32_e32 v17, 2, v2
	v_xor_b32_e32 v2, 2, v0
	v_cmp_lt_i32_e32 vcc, v2, v1
	s_waitcnt lgkmcnt(0)
	s_add_u32 s33, s2, 0x52800000
	s_addc_u32 s35, s3, 0
	v_cndmask_b32_e32 v2, v0, v2, vcc
	v_lshlrev_b32_e32 v34, 2, v2
	v_xor_b32_e32 v2, 4, v0
	v_cmp_lt_i32_e32 vcc, v2, v1
	s_ashr_i32 s21, s20, 31
	s_lshl_b64 s[2:3], s[20:21], 11
	v_cndmask_b32_e32 v2, v0, v2, vcc
	v_lshlrev_b32_e32 v35, 2, v2
	v_xor_b32_e32 v2, 8, v0
	v_cmp_lt_i32_e32 vcc, v2, v1
	s_add_u32 s22, s8, s2
	s_addc_u32 s23, s9, s3
	v_cndmask_b32_e32 v2, v0, v2, vcc
	v_lshlrev_b32_e32 v36, 2, v2
	v_xor_b32_e32 v2, 16, v0
	v_cmp_lt_i32_e32 vcc, v2, v1
	s_ashr_i32 s19, s18, 31
	s_lshl_b64 s[24:25], s[18:19], 11
	v_cndmask_b32_e32 v2, v0, v2, vcc
	v_lshlrev_b32_e32 v37, 2, v2
	v_xor_b32_e32 v2, 32, v0
	s_add_u32 s26, s10, s2
	v_cmp_lt_i32_e32 vcc, v2, v1
	s_addc_u32 s27, s11, s3
	s_add_u32 s36, s12, s2
	v_cndmask_b32_e32 v0, v0, v2, vcc
	v_lshlrev_b32_e32 v38, 2, v0
	v_lshl_add_u64 v[0:1], s[6:7], 0, v[96:97]
	v_lshl_add_u64 v[2:3], s[16:17], 0, v[96:97]
	v_lshlrev_b32_e32 v4, 3, v16
	v_mov_b32_e32 v5, v97
	s_addc_u32 s37, s13, s3
	s_brev_b32 s19, 42
	v_lshlrev_b32_e32 v6, 4, v16
	v_mov_b32_e32 v7, v97
	s_mov_b64 s[38:39], 0x200000
	s_mov_b32 s21, 0x200000
	s_mov_b64 s[40:41], 0x400000
	s_mov_b32 s54, 0x400000
	s_mov_b64 s[42:43], 0x600000
	s_mov_b32 s55, 0x600000
	v_mov_b32_e32 v39, 0x358637bd
	s_mov_b32 s56, 0xf800000
	v_mov_b32_e32 v40, 0x260
	s_mov_b64 s[44:45], 0xda000
	s_mov_b64 s[46:47], 0xdc000
	s_mov_b32 s57, 0xdc000
	s_mov_b64 s[48:49], 0xdb000
	s_mov_b32 s58, 0xdb000
	s_mov_b32 s59, 0x9000000

.LBB0_1179:
	s_add_u32 s2, s12, 0x54000000
	s_addc_u32 s3, s13, 0
	s_add_u32 s20, s14, 0xd100000
	s_addc_u32 s21, s15, 0
	s_abs_i32 s19, s18
	v_cvt_f32_u32_e32 v0, s19
	s_add_i32 s22, s18, 0x7fff
	s_sub_i32 s23, 0xffff8001, s18
	s_xor_b32 s18, s22, s18
	v_rcp_iflag_f32_e32 v0, v0
	s_max_i32 s22, s22, s23
	s_sub_i32 s23, 0, s19
	s_ashr_i32 s18, s18, 31
	v_mul_f32_e32 v0, 0x4f7ffffe, v0
	v_cvt_u32_f32_e32 v0, v0
	s_nop 0
	v_readfirstlane_b32 s24, v0
	s_mul_i32 s23, s23, s24
	s_mul_hi_u32 s23, s24, s23
	s_add_i32 s24, s24, s23
	s_mul_hi_u32 s23, s22, s24
	s_mul_i32 s24, s23, s19
	s_sub_i32 s22, s22, s24
	s_add_i32 s25, s23, 1
	s_sub_i32 s24, s22, s19
	s_cmp_ge_u32 s22, s19
	s_cselect_b32 s23, s25, s23
	s_cselect_b32 s22, s24, s22
	s_add_i32 s24, s23, 1
	s_cmp_ge_u32 s22, s19
	s_cselect_b32 s19, s24, s23
	s_xor_b32 s19, s19, s18
	s_sub_i32 s19, s19, s18
	s_mul_i32 s18, s19, s34
	s_add_i32 s19, s18, s19
	s_min_i32 s26, s19, 0x8000
	s_and_b32 s100, s34, 0xff
	s_lshr_b32 s101, s34, 8
	s_lshl_b32 s101, s101, 12
	s_mul_i32 s98, s100, 18
	s_add_i32 s98, s98, s101
	s_add_i32 s99, s100, 0xffffff40
	s_mul_i32 s99, s99, 10
	s_addk_i32 s99, 0xd80
	s_add_i32 s99, s99, s101
	s_cmpk_lt_i32 s100, 0xc0
	s_cselect_b32 s18, s98, s99
	s_cselect_b32 s98, 18, 10
	s_add_i32 s26, s18, s98
	s_cmp_lt_i32 s18, s26
	s_cselect_b64 s[22:23], -1, 0
	s_cmp_ge_i32 s18, s26
	s_cbranch_scc1 .LBB0_1181
	s_ashr_i32 s19, s18, 31
	s_lshl_b64 s[24:25], s[18:19], 11
	s_add_u32 s34, s20, s24
	s_addc_u32 s35, s21, s25
	s_add_u32 s24, s2, s24
	s_addc_u32 s25, s3, s25
	global_load_dwordx4 v[84:87], v96, s[24:25]
	global_load_dwordx4 v[80:83], v96, s[24:25] offset:1024
	global_load_dwordx4 v[92:95], v96, s[34:35]
	global_load_dwordx4 v[88:91], v96, s[34:35] offset:1024

.LBB0_1395:
	v_readlane_b32 s20, v255, 2
	v_readlane_b32 s21, v255, 3
	s_lshl_b32 s48, s3, 3
	s_lshl_b32 s18, s2, 3
	s_mov_b64 s[2:3], s[20:21]
	s_load_dwordx2 s[12:13], s[2:3], 0xf0
	s_mov_b64 s[2:3], s[20:21]
	s_load_dwordx2 s[14:15], s[2:3], 0xf0
	s_mov_b64 s[2:3], s[20:21]
	s_load_dwordx2 s[10:11], s[2:3], 0xf0
	s_mov_b64 s[2:3], s[20:21]
	s_ashr_i32 s6, s6, 6
	s_add_i32 s48, s48, s6
	s_load_dwordx2 s[2:3], s[2:3], 0xf0
	s_mov_b64 s[6:7], s[20:21]
	s_mov_b64 s[8:9], s[20:21]
	s_load_dwordx2 s[6:7], s[6:7], 0x50
	s_mov_b64 s[16:17], s[20:21]
	s_load_dwordx2 s[8:9], s[8:9], 0xf0
	s_load_dwordx2 s[16:17], s[16:17], 0x50
	s_waitcnt lgkmcnt(0)
	s_add_u32 s46, s2, 0x100000
	s_addc_u32 s47, s3, 0
	s_add_u32 s6, s6, 0x7000
	s_addc_u32 s7, s7, 0
	s_add_u32 s16, s16, 0x8000
	s_addc_u32 s17, s17, 0
	s_and_b32 s98, s48, 0xff
	s_lshr_b32 s99, s48, 8
	s_lshl_b32 s99, s99, 6
	s_sub_i32 s19, 0xff, s98
	s_add_i32 s19, s19, s99
	s_cmpk_lt_u32 s98, 0xc0
	s_cselect_b32 s19, 0x200, s19
	v_and_b32_e32 v16, 63, v0
	s_mov_b64 s[2:3], s[20:21]
	s_add_i32 s20, s19, 0x8000
	s_cmp_gt_i32 s20, 0x81ff
	v_lshlrev_b32_e32 v96, 4, v16
	s_cbranch_scc1 .LBB0_1398
	v_mbcnt_hi_u32_b32 v0, -1, v252
	v_and_b32_e32 v1, 64, v0
	v_add_u32_e32 v1, 64, v1
	v_xor_b32_e32 v2, 1, v0
	v_cmp_lt_i32_e32 vcc, v2, v1
	s_load_dwordx2 s[2:3], s[2:3], 0xf0
	v_mov_b32_e32 v97, 0
	v_cndmask_b32_e32 v2, v0, v2, vcc
	v_lshlrev_b32_e32 v17, 2, v2
	v_xor_b32_e32 v2, 2, v0
	v_cmp_lt_i32_e32 vcc, v2, v1
	s_ashr_i32 s21, s20, 31
	v_lshl_add_u64 v[4:5], s[6:7], 0, v[96:97]
	v_cndmask_b32_e32 v2, v0, v2, vcc
	v_lshlrev_b32_e32 v34, 2, v2
	v_xor_b32_e32 v2, 4, v0
	v_cmp_lt_i32_e32 vcc, v2, v1
	v_lshl_add_u64 v[6:7], s[16:17], 0, v[96:97]
	v_lshlrev_b32_e32 v10, 3, v16
	v_cndmask_b32_e32 v2, v0, v2, vcc
	v_lshlrev_b32_e32 v35, 2, v2
	v_xor_b32_e32 v2, 8, v0
	v_cmp_lt_i32_e32 vcc, v2, v1
	v_mov_b32_e32 v11, v97
	s_mov_b32 s49, 0x400000
	v_cndmask_b32_e32 v2, v0, v2, vcc
	v_lshlrev_b32_e32 v36, 2, v2
	v_xor_b32_e32 v2, 16, v0
	v_cmp_lt_i32_e32 vcc, v2, v1
	s_mov_b32 s50, 0x600000
	s_mov_b32 s51, 0x800000
	v_cndmask_b32_e32 v2, v0, v2, vcc
	v_lshlrev_b32_e32 v37, 2, v2
	v_xor_b32_e32 v2, 32, v0
	v_cmp_lt_i32_e32 vcc, v2, v1
	s_mov_b32 s52, 0xa00000
	s_mov_b32 s53, 0xc00000
	v_cndmask_b32_e32 v0, v0, v2, vcc
	v_lshlrev_b32_e32 v38, 2, v0
	s_waitcnt lgkmcnt(0)
	v_lshl_add_u64 v[0:1], s[2:3], 0, v[96:97]
	s_mov_b64 s[2:3], 0x52800000
	v_lshl_add_u64 v[8:9], v[0:1], 0, s[2:3]
	s_lshl_b64 s[2:3], s[20:21], 11
	s_add_u32 s22, s8, s2
	s_addc_u32 s23, s9, s3
	s_ashr_i32 s19, s18, 31
	s_lshl_b64 s[24:25], s[18:19], 11
	s_add_u32 s26, s10, s2
	s_addc_u32 s27, s11, s3
	s_add_u32 s36, s12, s2
	s_addc_u32 s37, s13, s3
	s_brev_b32 s19, 42
	s_mov_b32 s21, 0x200000
	s_mov_b32 s54, 0xe00000
	s_mov_b32 s55, 0x1000000
	s_mov_b32 s56, 0x1200000
	s_mov_b32 s57, 0x1400000
	v_mov_b32_e32 v39, 0x358637bd
	s_mov_b32 s58, 0xf800000
	v_mov_b32_e32 v40, 0x260
	v_lshlrev_b32_e32 v12, 4, v16
	v_mov_b32_e32 v13, v97
	s_mov_b64 s[38:39], 0xdd000
	s_mov_b32 s59, 0xdd000
	s_mov_b64 s[40:41], 0x1b1000
	s_mov_b32 s60, 0x1b1000
	s_mov_b64 s[42:43], 0x1b0000
	s_mov_b32 s61, 0x1b0000
	s_mov_b32 s62, 0x9000000

.LBB0_2009:
	v_readlane_b32 s20, v255, 2
	v_readlane_b32 s21, v255, 3
	s_lshl_b32 s48, s3, 3
	s_lshl_b32 s18, s2, 3
	s_mov_b64 s[2:3], s[20:21]
	s_load_dwordx2 s[12:13], s[2:3], 0xf0
	s_mov_b64 s[2:3], s[20:21]
	s_load_dwordx2 s[14:15], s[2:3], 0xf0
	s_mov_b64 s[2:3], s[20:21]
	s_load_dwordx2 s[10:11], s[2:3], 0xf0
	s_mov_b64 s[2:3], s[20:21]
	s_ashr_i32 s6, s6, 6
	s_add_i32 s48, s48, s6
	s_load_dwordx2 s[2:3], s[2:3], 0xf0
	s_mov_b64 s[6:7], s[20:21]
	s_mov_b64 s[8:9], s[20:21]
	s_load_dwordx2 s[6:7], s[6:7], 0x50
	s_mov_b64 s[16:17], s[20:21]
	s_load_dwordx2 s[8:9], s[8:9], 0xf0
	s_load_dwordx2 s[16:17], s[16:17], 0x50
	s_waitcnt lgkmcnt(0)
	s_add_u32 s46, s2, 0x100000
	s_addc_u32 s47, s3, 0
	s_add_u32 s6, s6, 0x9000
	s_addc_u32 s7, s7, 0
	s_add_u32 s16, s16, 0xa000
	s_addc_u32 s17, s17, 0
	s_and_b32 s98, s48, 0xff
	s_lshr_b32 s99, s48, 8
	s_lshl_b32 s99, s99, 6
	s_sub_i32 s19, 0xff, s98
	s_add_i32 s19, s19, s99
	s_cmpk_lt_u32 s98, 0xc0
	s_cselect_b32 s19, 0x200, s19
	v_and_b32_e32 v16, 63, v0
	s_mov_b64 s[2:3], s[20:21]
	s_add_i32 s20, s19, 0x8000
	s_cmp_gt_i32 s20, 0x81ff
	v_lshlrev_b32_e32 v96, 4, v16
	s_cbranch_scc1 .LBB0_2012
	v_mbcnt_hi_u32_b32 v0, -1, v252
	v_and_b32_e32 v1, 64, v0
	v_add_u32_e32 v1, 64, v1
	v_xor_b32_e32 v2, 1, v0
	v_cmp_lt_i32_e32 vcc, v2, v1
	s_load_dwordx2 s[2:3], s[2:3], 0xf0
	v_mov_b32_e32 v97, 0
	v_cndmask_b32_e32 v2, v0, v2, vcc
	v_lshlrev_b32_e32 v17, 2, v2
	v_xor_b32_e32 v2, 2, v0
	v_cmp_lt_i32_e32 vcc, v2, v1
	s_waitcnt lgkmcnt(0)
	v_lshl_add_u64 v[4:5], s[2:3], 0, v[96:97]
	s_mov_b64 s[2:3], 0x52800000
	v_cndmask_b32_e32 v2, v0, v2, vcc
	v_lshlrev_b32_e32 v36, 2, v2
	v_xor_b32_e32 v2, 4, v0
	v_cmp_lt_i32_e32 vcc, v2, v1
	s_ashr_i32 s21, s20, 31
	v_lshl_add_u64 v[4:5], v[4:5], 0, s[2:3]
	v_cndmask_b32_e32 v2, v0, v2, vcc
	v_lshlrev_b32_e32 v37, 2, v2
	v_xor_b32_e32 v2, 8, v0
	v_cmp_lt_i32_e32 vcc, v2, v1
	s_lshl_b64 s[2:3], s[20:21], 11
	s_add_u32 s22, s8, s2
	v_cndmask_b32_e32 v2, v0, v2, vcc
	v_lshlrev_b32_e32 v38, 2, v2
	v_xor_b32_e32 v2, 16, v0
	v_cmp_lt_i32_e32 vcc, v2, v1
	s_addc_u32 s23, s9, s3
	s_ashr_i32 s19, s18, 31
	v_cndmask_b32_e32 v2, v0, v2, vcc
	s_lshl_b64 s[24:25], s[18:19], 11
	v_lshlrev_b32_e32 v39, 2, v2
	v_xor_b32_e32 v2, 32, v0
	s_add_u32 s26, s10, s2
	v_cmp_lt_i32_e32 vcc, v2, v1
	s_addc_u32 s27, s11, s3
	s_add_u32 s36, s12, s2
	v_cndmask_b32_e32 v0, v0, v2, vcc
	v_lshlrev_b32_e32 v40, 2, v0
	v_lshl_add_u64 v[0:1], s[6:7], 0, v[96:97]
	v_lshl_add_u64 v[2:3], s[16:17], 0, v[96:97]
	v_lshlrev_b32_e32 v6, 3, v16
	v_mov_b32_e32 v7, v97
	s_addc_u32 s37, s13, s3
	s_brev_b32 s19, 42
	s_mov_b32 s21, 0x200000
	s_mov_b32 s33, 0x400000
	s_mov_b32 s34, 0x600000
	s_mov_b32 s35, 0x800000
	s_mov_b32 s49, 0xa00000
	s_mov_b32 s50, 0xc00000
	s_mov_b32 s51, 0xe00000
	v_mov_b32_e32 v41, 0x358637bd
	s_mov_b32 s52, 0xf800000
	v_mov_b32_e32 v42, 0x260
	v_lshlrev_b32_e32 v8, 4, v16
	v_mov_b32_e32 v9, v97
	s_mov_b64 s[38:39], 0x1b2000
	s_mov_b64 s[40:41], 0x1b4000
	s_mov_b32 s53, 0x1b4000
	s_mov_b64 s[42:43], 0x1b3000
	s_mov_b32 s54, 0x1b3000
	s_mov_b32 s55, 0x9000000

.LBB0_2228:
	v_readlane_b32 s20, v255, 2
	v_readlane_b32 s21, v255, 3
	s_lshl_b32 s48, s3, 3
	s_lshl_b32 s18, s2, 3
	s_mov_b64 s[2:3], s[20:21]
	s_load_dwordx2 s[12:13], s[2:3], 0xf0
	s_mov_b64 s[2:3], s[20:21]
	s_load_dwordx2 s[14:15], s[2:3], 0xf0
	s_mov_b64 s[2:3], s[20:21]
	s_load_dwordx2 s[10:11], s[2:3], 0xf0
	s_mov_b64 s[2:3], s[20:21]
	s_ashr_i32 s6, s6, 6
	s_add_i32 s48, s48, s6
	s_load_dwordx2 s[2:3], s[2:3], 0xf0
	s_mov_b64 s[6:7], s[20:21]
	s_mov_b64 s[8:9], s[20:21]
	s_load_dwordx2 s[6:7], s[6:7], 0x50
	s_mov_b64 s[16:17], s[20:21]
	s_load_dwordx2 s[8:9], s[8:9], 0xf0
	s_load_dwordx2 s[16:17], s[16:17], 0x50
	s_waitcnt lgkmcnt(0)
	s_add_u32 s46, s2, 0x100000
	s_addc_u32 s47, s3, 0
	s_add_u32 s6, s6, 0xb000
	s_addc_u32 s7, s7, 0
	s_add_u32 s16, s16, 0xc000
	s_addc_u32 s17, s17, 0
	s_and_b32 s98, s48, 0xff
	s_lshr_b32 s99, s48, 8
	s_lshl_b32 s99, s99, 6
	s_sub_i32 s19, 0xff, s98
	s_add_i32 s19, s19, s99
	s_cmpk_lt_u32 s98, 0xc0
	s_cselect_b32 s19, 0x200, s19
	v_and_b32_e32 v16, 63, v0
	s_mov_b64 s[2:3], s[20:21]
	s_add_i32 s20, s19, 0x8000
	s_cmp_gt_i32 s20, 0x81ff
	v_lshlrev_b32_e32 v96, 4, v16
	s_cbranch_scc1 .LBB0_2231
	v_mbcnt_hi_u32_b32 v0, -1, v252
	v_and_b32_e32 v1, 64, v0
	v_add_u32_e32 v1, 64, v1
	v_xor_b32_e32 v2, 1, v0
	v_cmp_lt_i32_e32 vcc, v2, v1
	s_load_dwordx2 s[2:3], s[2:3], 0xf0
	v_mov_b32_e32 v97, 0
	v_cndmask_b32_e32 v2, v0, v2, vcc
	v_lshlrev_b32_e32 v17, 2, v2
	v_xor_b32_e32 v2, 2, v0
	v_cmp_lt_i32_e32 vcc, v2, v1
	s_ashr_i32 s21, s20, 31
	v_lshl_add_u64 v[4:5], s[6:7], 0, v[96:97]
	v_cndmask_b32_e32 v2, v0, v2, vcc
	v_lshlrev_b32_e32 v34, 2, v2
	v_xor_b32_e32 v2, 4, v0
	v_cmp_lt_i32_e32 vcc, v2, v1
	v_lshl_add_u64 v[6:7], s[16:17], 0, v[96:97]
	v_lshlrev_b32_e32 v10, 3, v16
	v_cndmask_b32_e32 v2, v0, v2, vcc
	v_lshlrev_b32_e32 v35, 2, v2
	v_xor_b32_e32 v2, 8, v0
	v_cmp_lt_i32_e32 vcc, v2, v1
	v_mov_b32_e32 v11, v97
	s_mov_b32 s49, 0x400000
	v_cndmask_b32_e32 v2, v0, v2, vcc
	v_lshlrev_b32_e32 v36, 2, v2
	v_xor_b32_e32 v2, 16, v0
	v_cmp_lt_i32_e32 vcc, v2, v1
	s_mov_b32 s50, 0x600000
	s_mov_b32 s51, 0x800000
	v_cndmask_b32_e32 v2, v0, v2, vcc
	v_lshlrev_b32_e32 v37, 2, v2
	v_xor_b32_e32 v2, 32, v0
	v_cmp_lt_i32_e32 vcc, v2, v1
	s_mov_b32 s52, 0xa00000
	s_mov_b32 s53, 0xc00000
	v_cndmask_b32_e32 v0, v0, v2, vcc
	v_lshlrev_b32_e32 v38, 2, v0
	s_waitcnt lgkmcnt(0)
	v_lshl_add_u64 v[0:1], s[2:3], 0, v[96:97]
	s_mov_b64 s[2:3], 0x52800000
	v_lshl_add_u64 v[8:9], v[0:1], 0, s[2:3]
	s_lshl_b64 s[2:3], s[20:21], 11
	s_add_u32 s22, s8, s2
	s_addc_u32 s23, s9, s3
	s_ashr_i32 s19, s18, 31
	s_lshl_b64 s[24:25], s[18:19], 11
	s_add_u32 s26, s10, s2
	s_addc_u32 s27, s11, s3
	s_add_u32 s36, s12, s2
	s_addc_u32 s37, s13, s3
	s_brev_b32 s19, 42
	s_mov_b32 s21, 0x200000
	s_mov_b32 s54, 0xe00000
	s_mov_b32 s55, 0x1000000
	s_mov_b32 s56, 0x1200000
	s_mov_b32 s57, 0x1400000
	v_mov_b32_e32 v39, 0x358637bd
	s_mov_b32 s58, 0xf800000
	v_mov_b32_e32 v40, 0x260
	v_lshlrev_b32_e32 v12, 4, v16
	v_mov_b32_e32 v13, v97
	s_mov_b64 s[38:39], 0x1b5000
	s_mov_b32 s59, 0x1b5000
	s_mov_b64 s[40:41], 0x289000
	s_mov_b32 s60, 0x289000
	s_mov_b64 s[42:43], 0x288000
	s_mov_b32 s61, 0x288000
	s_mov_b32 s62, 0x9000000

.LBB0_2658:
	v_readlane_b32 s0, v255, 2
	v_readlane_b32 s1, v255, 3
	s_lshl_b32 s34, s3, 3
	s_lshl_b32 s18, s2, 3
	s_mov_b64 s[2:3], s[0:1]
	s_load_dwordx2 s[12:13], s[2:3], 0xf0
	s_mov_b64 s[2:3], s[0:1]
	s_load_dwordx2 s[14:15], s[2:3], 0xf0
	s_mov_b64 s[2:3], s[0:1]
	s_load_dwordx2 s[10:11], s[2:3], 0xf0
	s_mov_b64 s[2:3], s[0:1]
	s_ashr_i32 s6, s6, 6
	s_add_i32 s34, s34, s6
	s_load_dwordx2 s[2:3], s[2:3], 0xf0
	s_mov_b64 s[6:7], s[0:1]
	s_mov_b64 s[8:9], s[0:1]
	s_load_dwordx2 s[6:7], s[6:7], 0x50
	s_mov_b64 s[16:17], s[0:1]
	s_load_dwordx2 s[8:9], s[8:9], 0xf0
	s_load_dwordx2 s[16:17], s[16:17], 0x50
	s_waitcnt lgkmcnt(0)
	s_add_u32 s52, s2, 0x100000
	s_addc_u32 s53, s3, 0
	s_add_u32 s6, s6, 0xd000
	s_addc_u32 s7, s7, 0
	s_add_u32 s16, s16, 0xe000
	s_addc_u32 s17, s17, 0
	s_and_b32 s98, s34, 0xff
	s_lshr_b32 s99, s34, 8
	s_lshl_b32 s99, s99, 6
	s_sub_i32 s19, 0xff, s98
	s_add_i32 s19, s19, s99
	s_cmpk_lt_u32 s98, 0xc0
	s_cselect_b32 s19, 0x200, s19
	v_and_b32_e32 v16, 63, v0
	s_add_i32 s20, s19, 0x8000
	s_mov_b64 s[2:3], s[0:1]
	s_cmp_gt_i32 s20, 0x81ff
	v_lshlrev_b32_e32 v96, 4, v16
	s_cbranch_scc1 .LBB0_2661
	v_mbcnt_hi_u32_b32 v0, -1, v252
	v_and_b32_e32 v1, 64, v0
	v_xor_b32_e32 v2, 1, v0
	v_add_u32_e32 v1, 64, v1
	v_cmp_lt_i32_e32 vcc, v2, v1
	s_load_dwordx2 s[2:3], s[2:3], 0xf0
	v_mov_b32_e32 v97, 0
	v_cndmask_b32_e32 v2, v0, v2, vcc
	v_lshlrev_b32_e32 v17, 2, v2
	v_xor_b32_e32 v2, 2, v0
	v_cmp_lt_i32_e32 vcc, v2, v1
	s_waitcnt lgkmcnt(0)
	s_add_u32 s33, s2, 0x52800000
	s_addc_u32 s35, s3, 0
	v_cndmask_b32_e32 v2, v0, v2, vcc
	v_lshlrev_b32_e32 v34, 2, v2
	v_xor_b32_e32 v2, 4, v0
	v_cmp_lt_i32_e32 vcc, v2, v1
	s_ashr_i32 s21, s20, 31
	s_lshl_b64 s[2:3], s[20:21], 11
	v_cndmask_b32_e32 v2, v0, v2, vcc
	v_lshlrev_b32_e32 v35, 2, v2
	v_xor_b32_e32 v2, 8, v0
	v_cmp_lt_i32_e32 vcc, v2, v1
	s_add_u32 s22, s8, s2
	s_addc_u32 s23, s9, s3
	v_cndmask_b32_e32 v2, v0, v2, vcc
	v_lshlrev_b32_e32 v36, 2, v2
	v_xor_b32_e32 v2, 16, v0
	v_cmp_lt_i32_e32 vcc, v2, v1
	s_ashr_i32 s19, s18, 31
	s_lshl_b64 s[24:25], s[18:19], 11
	v_cndmask_b32_e32 v2, v0, v2, vcc
	v_lshlrev_b32_e32 v37, 2, v2
	v_xor_b32_e32 v2, 32, v0
	s_add_u32 s26, s10, s2
	v_cmp_lt_i32_e32 vcc, v2, v1
	s_addc_u32 s27, s11, s3
	s_add_u32 s36, s12, s2
	v_cndmask_b32_e32 v0, v0, v2, vcc
	v_lshlrev_b32_e32 v38, 2, v0
	v_lshl_add_u64 v[0:1], s[6:7], 0, v[96:97]
	v_lshl_add_u64 v[2:3], s[16:17], 0, v[96:97]
	v_lshlrev_b32_e32 v4, 3, v16
	v_mov_b32_e32 v5, v97
	s_addc_u32 s37, s13, s3
	s_brev_b32 s19, 42
	v_lshlrev_b32_e32 v6, 4, v16
	v_mov_b32_e32 v7, v97
	s_mov_b64 s[38:39], 0x200000
	s_mov_b32 s21, 0x200000
	s_mov_b64 s[40:41], 0x400000
	s_mov_b32 s54, 0x400000
	s_mov_b64 s[42:43], 0x600000
	s_mov_b32 s55, 0x600000
	v_mov_b32_e32 v39, 0x358637bd
	s_mov_b32 s56, 0xf800000
	v_mov_b32_e32 v40, 0x260
	s_mov_b64 s[44:45], 0x28a000
	s_mov_b64 s[46:47], 0x28c000
	s_mov_b32 s57, 0x28c000
	s_mov_b64 s[48:49], 0x28b000
	s_mov_b32 s58, 0x28b000
	s_mov_b32 s59, 0x9000000

.LBB0_2877:
	v_readlane_b32 s0, v255, 2
	v_readlane_b32 s1, v255, 3
	s_ashr_i32 s11, s5, 6
	s_lshl_b32 s33, s4, 3
	s_mov_b64 s[4:5], s[0:1]
	s_mov_b64 s[6:7], s[0:1]
	s_load_dwordx2 s[4:5], s[4:5], 0xf0
	s_mov_b64 s[8:9], s[0:1]
	s_load_dwordx2 s[6:7], s[6:7], 0xf0
	s_mov_b64 s[12:13], s[0:1]
	s_load_dwordx2 s[8:9], s[8:9], 0xe8
	s_load_dwordx2 s[14:15], s[12:13], 0xf0
	s_mov_b64 s[12:13], s[0:1]
	s_load_dwordx2 s[16:17], s[12:13], 0x50
	s_add_i32 s33, s33, s11
	s_lshl_b32 s12, s10, 3
	s_waitcnt lgkmcnt(0)
	s_add_u32 s50, s14, 0x100000
	s_addc_u32 s51, s15, 0
	s_add_u32 s10, s16, 0xf000
	s_addc_u32 s11, s17, 0
	s_and_b32 s98, s33, 0xff
	s_lshr_b32 s99, s33, 8
	s_lshl_b32 s99, s99, 6
	s_sub_i32 s13, 0xff, s98
	s_add_i32 s13, s13, s99
	s_cmpk_lt_u32 s98, 0xc0
	s_cselect_b32 s13, 0x200, s13
	v_and_b32_e32 v16, 63, v0
	s_add_i32 s14, s13, 0x8000
	s_cmp_gt_i32 s14, 0x81ff
	v_lshlrev_b32_e32 v64, 4, v16
	s_cbranch_scc1 .LBB0_2880
	v_mbcnt_hi_u32_b32 v0, -1, v252
	v_and_b32_e32 v1, 64, v0
	v_xor_b32_e32 v2, 1, v0
	v_add_u32_e32 v1, 64, v1
	v_cmp_lt_i32_e32 vcc, v2, v1
	s_load_dwordx2 s[0:1], s[0:1], 0xf0
	v_mov_b32_e32 v65, 0
	v_cndmask_b32_e32 v2, v0, v2, vcc
	v_lshlrev_b32_e32 v17, 2, v2
	v_xor_b32_e32 v2, 2, v0
	v_cmp_lt_i32_e32 vcc, v2, v1
	s_waitcnt lgkmcnt(0)
	s_add_u32 s34, s0, 0x52800000
	s_addc_u32 s35, s1, 0
	v_cndmask_b32_e32 v2, v0, v2, vcc
	v_lshlrev_b32_e32 v24, 2, v2
	v_xor_b32_e32 v2, 4, v0
	v_cmp_lt_i32_e32 vcc, v2, v1
	s_ashr_i32 s15, s14, 31
	s_lshl_b64 s[0:1], s[14:15], 12
	v_cndmask_b32_e32 v2, v0, v2, vcc
	v_lshlrev_b32_e32 v25, 2, v2
	v_xor_b32_e32 v2, 8, v0
	v_cmp_lt_i32_e32 vcc, v2, v1
	s_add_u32 s0, s8, s0
	s_addc_u32 s1, s9, s1
	v_cndmask_b32_e32 v2, v0, v2, vcc
	v_lshlrev_b32_e32 v26, 2, v2
	v_xor_b32_e32 v2, 16, v0
	v_cmp_lt_i32_e32 vcc, v2, v1
	s_ashr_i32 s13, s12, 31
	v_lshl_add_u64 v[6:7], s[0:1], 0, v[64:65]
	v_cndmask_b32_e32 v2, v0, v2, vcc
	v_lshlrev_b32_e32 v27, 2, v2
	v_xor_b32_e32 v2, 32, v0
	v_cmp_lt_i32_e32 vcc, v2, v1
	s_lshl_b64 s[16:17], s[12:13], 12
	s_lshl_b64 s[0:1], s[14:15], 11
	v_cndmask_b32_e32 v0, v0, v2, vcc
	s_add_u32 s0, s4, s0
	v_lshlrev_b32_e32 v28, 2, v0
	v_lshlrev_b32_e32 v0, 3, v16
	v_mov_b32_e32 v1, v65
	s_addc_u32 s1, s5, s1
	v_lshl_add_u64 v[0:1], s[0:1], 0, v[0:1]
	s_mov_b64 s[0:1], 0x54000000
	v_lshl_add_u64 v[4:5], s[10:11], 0, v[64:65]
	v_lshl_add_u64 v[8:9], v[0:1], 0, s[0:1]
	s_lshl_b64 s[18:19], s[12:13], 11
	v_lshlrev_b32_e32 v10, 4, v16
	v_mov_b32_e32 v11, v65
	s_mov_b64 s[20:21], 0x200000
	s_mov_b64 s[22:23], 0x400000
	s_mov_b64 s[24:25], 0x600000
	s_mov_b64 s[26:27], 0x800000
	s_mov_b64 s[36:37], 0xa00000
	s_mov_b64 s[38:39], 0xc00000
	s_mov_b64 s[40:41], 0xe00000
	s_mov_b64 s[42:43], 0x1000000
	s_mov_b64 s[44:45], 0x1200000
	s_mov_b64 s[46:47], 0x1400000
	s_mov_b32 s13, 0x200000
	s_mov_b32 s15, 0x400000
	s_mov_b32 s52, 0x600000
	s_mov_b32 s53, 0x800000
	s_mov_b32 s54, 0xa00000
	s_mov_b32 s55, 0xc00000
	s_mov_b32 s56, 0xe00000
	s_mov_b32 s57, 0x1000000
	s_mov_b32 s58, 0x1200000
	s_mov_b32 s59, 0x1400000
	v_mov_b32_e32 v29, 0x358637bd
	s_mov_b32 s60, 0xf800000
	v_mov_b32_e32 v30, 0x260
	s_mov_b64 s[48:49], 0x28d000
	s_mov_b32 s61, 0x28d000

.LBB0_2880:
	s_add_u32 s0, s4, 0x54000000
	s_addc_u32 s1, s5, 0
	s_add_u32 s14, s6, 0xd100000
	s_addc_u32 s15, s7, 0
	s_abs_i32 s13, s12
	v_cvt_f32_u32_e32 v0, s13
	s_add_i32 s16, s12, 0x7fff
	s_sub_i32 s17, 0xffff8001, s12
	s_xor_b32 s12, s16, s12
	v_rcp_iflag_f32_e32 v0, v0
	s_max_i32 s16, s16, s17
	s_sub_i32 s17, 0, s13
	s_ashr_i32 s12, s12, 31
	v_mul_f32_e32 v0, 0x4f7ffffe, v0
	v_cvt_u32_f32_e32 v0, v0
	s_nop 0
	v_readfirstlane_b32 s18, v0
	s_mul_i32 s17, s17, s18
	s_mul_hi_u32 s17, s18, s17
	s_add_i32 s18, s18, s17
	s_mul_hi_u32 s17, s16, s18
	s_mul_i32 s18, s17, s13
	s_sub_i32 s16, s16, s18
	s_add_i32 s19, s17, 1
	s_sub_i32 s18, s16, s13
	s_cmp_ge_u32 s16, s13
	s_cselect_b32 s17, s19, s17
	s_cselect_b32 s16, s18, s16
	s_add_i32 s18, s17, 1
	s_cmp_ge_u32 s16, s13
	s_cselect_b32 s13, s18, s17
	s_xor_b32 s13, s13, s12
	s_sub_i32 s13, s13, s12
	s_mul_i32 s12, s13, s33
	s_add_i32 s13, s12, s13
	s_min_i32 s20, s13, 0x8000
	s_and_b32 s100, s33, 0xff
	s_lshr_b32 s101, s33, 8
	s_lshl_b32 s101, s101, 12
	s_mul_i32 s98, s100, 18
	s_add_i32 s98, s98, s101
	s_add_i32 s99, s100, 0xffffff40
	s_mul_i32 s99, s99, 10
	s_addk_i32 s99, 0xd80
	s_add_i32 s99, s99, s101
	s_cmpk_lt_i32 s100, 0xc0
	s_cselect_b32 s12, s98, s99
	s_cselect_b32 s98, 18, 10
	s_add_i32 s20, s12, s98
	s_cmp_lt_i32 s12, s20
	s_cselect_b64 s[16:17], -1, 0
	s_cmp_ge_i32 s12, s20
	s_cbranch_scc1 .LBB0_2882
	s_ashr_i32 s13, s12, 31
	s_lshl_b64 s[18:19], s[12:13], 11
	s_add_u32 s22, s14, s18
	s_addc_u32 s23, s15, s19
	s_add_u32 s18, s0, s18
	s_addc_u32 s19, s1, s19
	global_load_dwordx4 v[52:55], v64, s[18:19]
	global_load_dwordx4 v[48:51], v64, s[18:19] offset:1024
	global_load_dwordx4 v[60:63], v64, s[22:23]
	global_load_dwordx4 v[56:59], v64, s[22:23] offset:1024
